# v73 + grid barrier: the first workgroup of each XCD to arrive also issues an (unwaited) L2 write-back, so the XCD leader's release fence finds less dirty data
# speedup vs baseline: 1.0023x; 1.0023x over previous
.LBB0_872:
	s_or_b64 exec, exec, s[2:3]
	v_cvt_f32_u32_e32 v4, v2
	s_waitcnt vmcnt(0)
	v_readfirstlane_b32 s2, v3
	v_sub_u32_e32 v3, 0, v2
	v_rcp_iflag_f32_e32 v4, v4
	v_add_u32_e32 v5, s2, v1
	v_mul_f32_e32 v4, 0x4f7ffffe, v4
	v_cvt_u32_f32_e32 v4, v4
	v_mul_lo_u32 v1, v3, v4
	v_mul_hi_u32 v1, v4, v1
	v_add_u32_e32 v1, v4, v1
	v_mul_hi_u32 v1, v5, v1
	v_mul_lo_u32 v3, v1, v2
	v_sub_u32_e32 v3, v5, v3
	v_add_u32_e32 v4, 1, v1
	v_cmp_ge_u32_e32 vcc, v3, v2
	s_nop 1
	v_cndmask_b32_e32 v1, v1, v4, vcc
	v_sub_u32_e32 v4, v3, v2
	v_cndmask_b32_e32 v3, v3, v4, vcc
	v_add_u32_e32 v4, 1, v1
	v_cmp_ge_u32_e32 vcc, v3, v2
	v_add_u32_e32 v3, 1, v5
	s_nop 0
	v_cndmask_b32_e32 v1, v1, v4, vcc
	v_mul_lo_u32 v4, v2, v1
	v_add_u32_e32 v2, v4, v2
	v_cmp_ne_u32_e32 vcc, v3, v2
	s_and_saveexec_b64 s[2:3], vcc
	s_xor_b64 s[2:3], exec, s[2:3]
	s_cbranch_execz .LBB0_886
	v_cmp_eq_u32_e32 vcc, v5, v4
	s_cbranch_vccz .Lbar_nofirst
	buffer_wbl2 sc1
.Lbar_nofirst:
	v_readlane_b32 s4, v253, 46
	v_readlane_b32 s5, v253, 47
	s_waitcnt lgkmcnt(0)
	s_nop 3
	global_load_dword v0, v161, s[4:5] sc1
	s_waitcnt vmcnt(0)
	v_cmp_eq_u32_e32 vcc, v0, v1
	s_and_saveexec_b64 s[4:5], vcc
	s_cbranch_execz .LBB0_885
	s_mov_b32 s12, 1
	s_mov_b64 s[6:7], 0
	s_branch .LBB0_876
